# FoX trip loop: leftover hazard nops and the m0 save/restore moves around the 4 LDS-DMA issues removed
# speedup vs baseline: 1.0028x; 1.0028x over previous
; #define ATT_WAIT_BAR() asm volatile("s_waitcnt vmcnt(0) lgkmcnt(0)\n\ts_barrier" ::: "memory")
; __device__ __forceinline__ void prompt_unit_fox(const Args& a, int l, int b, int h, int qb, LAS unsigned char* lds) {
;     ...
;         ATT_WAIT_BAR();
;         if (jp >= 1) ATT_DMA2(jp - 1, slot == 2 ? 0 : slot + 1);
.Lfox_top_l0:
	s_cmp_lg_u32 s90, 0
	s_cbranch_scc0 .LBB0_343
	s_add_i32 s80, s90, -1
	s_mov_b32 s81, s87
	s_lshl_b32 s3, s75, 14
	s_lshl_b64 s[80:81], s[80:81], 18
	s_add_i32 s33, s3, 0x4000
	s_cmp_lg_u32 s75, 2
	s_cselect_b32 s33, s33, 0
	v_lshl_add_u64 v[244:245], v[176:177], 0, s[80:81]
	s_add_i32 s82, s79, s33
	s_mov_b32 m0, s82
	s_nop 0
	global_load_lds_dwordx4 v[244:245], off
	s_mov_b64 s[96:97], 0x20000
	v_lshl_add_u64 v[244:245], v[244:245], 0, s[96:97]
	s_add_i32 s82, s84, s33
	s_mov_b32 m0, s82
	s_nop 0
	global_load_lds_dwordx4 v[244:245], off
	v_lshl_add_u64 v[244:245], v[178:179], 0, s[80:81]
	s_add_i32 s80, s85, s33
	s_mov_b32 m0, s80
	s_nop 0
	global_load_lds_dwordx4 v[244:245], off
	v_lshl_add_u64 v[244:245], v[244:245], 0, s[96:97]
	s_add_i32 s33, s76, s33
	s_mov_b32 m0, s33
	s_nop 0
	global_load_lds_dwordx4 v[244:245], off
	s_cbranch_execnz .LBB0_315

; __device__ __forceinline__ int crow(int r, int hi) { return (r & 3) + 8 * (r >> 2) + 4 * hi; }
; __device__ __forceinline__ float swap_max(float m) { auto rr = __builtin_amdgcn_permlane32_swap(__float_as_uint(m), __float_as_uint(m), false, false); return fmaxf(__uint_as_float(rr[0]), __uint_as_float(rr[1])); }
; __device__ __forceinline__ float max3f(float a, float b, float c) { return __builtin_fmaxf(__builtin_fmaxf(a, b), c); }
;     bf16x8 kf[8]; kfrags(kf, kslot, r32, hi);
;     f32x16 p0, p1;
; #pragma unroll
;     for (int g = 0; g < 4; ++g) { const f32x4 c0 = ld4(ckt + 8 * g), c1 = ld4(ckt + 32 + 8 * g);
; #pragma unroll
;         for (int i = 0; i < 4; ++i) { p0[4 * g + i] = c0[i]; p1[4 * g + i] = c1[i]; } }
;     u32x4 kn = {0u, 0xBF800000u, 0xBF80BF80u, 0u}; if (hi) { kn.y = 0u; kn.z = 0u; }
;     const bf16x8 kneg = __builtin_bit_cast(bf16x8, kn);
;     p0 = __builtin_amdgcn_mfma_f32_32x32x16_bf16(kneg, st.mq, p0, 0, 0, 0);
;     p1 = __builtin_amdgcn_mfma_f32_32x32x16_bf16(kneg, st.mq, p1, 0, 0, 0);
; #pragma unroll
;     for (int d0 = 0; d0 < 4; ++d0) {
;         p0 = __builtin_amdgcn_mfma_f32_32x32x16_bf16(kf[2 * d0], qr[d0], p0, 0, 0, 0);
;         p1 = __builtin_amdgcn_mfma_f32_32x32x16_bf16(kf[2 * d0 + 1], qr[d0], p1, 0, 0, 0);
;     }
;     __builtin_amdgcn_sched_barrier(0);
;     if (LEVEL == 2) { asm volatile("" :: "v"(p0), "v"(p1)); return; }
;     if (masked) {
;         asm volatile("; masked tile" ::: "memory");
; #pragma unroll
;         for (int r = 0; r < 16; ++r) { const int kv = crow(r, hi); if (kv >= qlim) p0[r] = NEG; if (kv + 32 >= qlim) p1[r] = NEG; }
;     }
;     float rm = max3f(p0[0], p1[0], p0[1]), rm2 = max3f(p1[1], p0[2], p1[2]);
; #pragma unroll
;     for (int r = 3; r < 15; r += 2) { rm = max3f(rm, p0[r], p1[r]); rm2 = max3f(rm2, p0[r + 1], p1[r + 1]); }
;     rm = max3f(rm, p0[15], p1[15]); rm = swap_max(max3f(rm, rm2, rm2));
;     if (first || __any(rm > FOX_THR)) {
;         const float dl = first ? rm : fmaxf(rm, 0.f);
;         st.m += dl; st.mq = make_mq(st.m, hi);
; #pragma unroll
;         for (int r = 0; r < 16; ++r) { p0[r] -= dl; p1[r] -= dl; }
.LBB0_317:
	s_add_i32 s80, s3, 0
	s_lshl_b32 s81, s90, 7
	v_add_u32_e32 v190, s3, v180
	s_cmp_ge_i32 s90, s89
	s_mov_b64 s[4:5], -1
	s_cbranch_scc0 .LBB0_328
	s_nop 11
	v_mov_b64_e32 v[66:67], v[50:51]
	v_mov_b64_e32 v[82:83], v[34:35]
	v_mov_b64_e32 v[162:163], v[158:159]
	s_cmp_lg_u32 s90, s89
	v_mov_b64_e32 v[64:65], v[48:49]
	v_mov_b64_e32 v[62:63], v[46:47]
	v_mov_b64_e32 v[60:61], v[44:45]
	v_mov_b64_e32 v[58:59], v[42:43]
	v_mov_b64_e32 v[56:57], v[40:41]
	v_mov_b64_e32 v[54:55], v[38:39]
	v_mov_b64_e32 v[52:53], v[36:37]
	v_mov_b64_e32 v[80:81], v[32:33]
	v_mov_b64_e32 v[78:79], v[30:31]
	v_mov_b64_e32 v[76:77], v[28:29]
	v_mov_b64_e32 v[74:75], v[26:27]
	v_mov_b64_e32 v[72:73], v[24:25]
	v_mov_b64_e32 v[70:71], v[22:23]
	v_mov_b64_e32 v[68:69], v[20:21]
	v_mov_b64_e32 v[160:161], v[156:157]
	v_mov_b32_e32 v194, v192
	v_mov_b32_e32 v191, v193
	s_cbranch_scc1 .LBB0_327
	v_lshl_add_u32 v196, s81, 2, v184
	s_andn2_b64 vcc, exec, s[94:95]
	v_add3_u32 v195, s80, v173, v188
	s_cbranch_vccnz .LBB0_325
	ds_read_b128 v[68:71], v196 offset:256
	ds_read_b128 v[72:75], v196 offset:288
	ds_read_b128 v[76:79], v196 offset:320
	ds_read_b128 v[80:83], v196 offset:352
	ds_read_b128 v[52:55], v196 offset:384
	ds_read_b128 v[56:59], v196 offset:416
	ds_read_b128 v[60:63], v196 offset:448
	ds_read_b128 v[64:67], v196 offset:480
	ds_read_b128 v[84:87], v195 offset:8192
	s_waitcnt lgkmcnt(5)
	v_mfma_f32_32x32x16_bf16 v[68:83], v[120:123], v[156:159], v[68:83]
	s_waitcnt lgkmcnt(0)
	v_mfma_f32_32x32x16_bf16 v[68:83], v[84:87], v[6:9], v[68:83]
	ds_read_b128 v[84:87], v195 offset:8704
	v_mfma_f32_32x32x16_bf16 v[52:67], v[120:123], v[156:159], v[52:67]
	s_waitcnt lgkmcnt(0)
	v_mfma_f32_32x32x16_bf16 v[52:67], v[84:87], v[6:9], v[52:67]
	ds_read_b128 v[84:87], v195 offset:10240
	s_waitcnt lgkmcnt(0)
	v_mfma_f32_32x32x16_bf16 v[68:83], v[84:87], v[10:13], v[68:83]
	ds_read_b128 v[84:87], v195 offset:10752
	s_waitcnt lgkmcnt(0)
	v_mfma_f32_32x32x16_bf16 v[52:67], v[84:87], v[10:13], v[52:67]
	ds_read_b128 v[84:87], v195 offset:12288
	s_waitcnt lgkmcnt(0)
	v_mfma_f32_32x32x16_bf16 v[68:83], v[84:87], v[14:17], v[68:83]
	ds_read_b128 v[84:87], v195 offset:12800
	s_waitcnt lgkmcnt(0)
	v_mfma_f32_32x32x16_bf16 v[52:67], v[84:87], v[14:17], v[52:67]
	ds_read_b128 v[84:87], v195 offset:14336
	s_waitcnt lgkmcnt(0)
	v_mfma_f32_32x32x16_bf16 v[68:83], v[84:87], v[116:119], v[68:83]
	ds_read_b128 v[84:87], v195 offset:14848
	s_waitcnt lgkmcnt(0)
	v_mfma_f32_32x32x16_bf16 v[52:67], v[84:87], v[116:119], v[52:67]
	s_and_b64 vcc, s[70:71], s[66:67]
	s_nop 7
	v_cndmask_b32_e32 v82, v82, v18, vcc
	s_and_b64 vcc, vcc, s[62:63]
	v_cndmask_b32_e32 v81, v81, v18, vcc
	s_and_b64 vcc, vcc, s[58:59]
	v_cndmask_b32_e32 v80, v80, v18, vcc
	s_and_b64 vcc, vcc, s[54:55]
	v_cndmask_b32_e32 v79, v79, v18, vcc
	s_and_b64 vcc, vcc, s[50:51]
	v_cndmask_b32_e32 v78, v78, v18, vcc
	s_and_b64 vcc, vcc, s[46:47]
	v_cndmask_b32_e32 v77, v77, v18, vcc
	s_and_b64 vcc, vcc, s[42:43]
	v_cndmask_b32_e32 v76, v76, v18, vcc
	s_and_b64 vcc, vcc, s[38:39]
	v_cndmask_b32_e32 v75, v75, v18, vcc
	s_and_b64 vcc, vcc, s[34:35]
	v_cndmask_b32_e32 v74, v74, v18, vcc
	s_and_b64 vcc, vcc, s[28:29]
	v_cndmask_b32_e32 v73, v73, v18, vcc
	s_and_b64 vcc, vcc, s[24:25]
	v_cndmask_b32_e64 v3, v68, v18, s[8:9]
	v_cndmask_b32_e32 v72, v72, v18, vcc
	s_and_b64 vcc, vcc, s[20:21]
	v_cndmask_b32_e64 v3, v3, v68, s[12:13]
	v_cndmask_b32_e64 v4, v18, v69, s[12:13]
	v_cndmask_b32_e32 v71, v71, v18, vcc
	s_and_b64 vcc, vcc, s[16:17]
	v_cndmask_b32_e32 v69, v69, v4, vcc
	v_cndmask_b32_e32 v68, v68, v3, vcc
	v_cndmask_b32_e32 v70, v70, v18, vcc
	s_and_b64 vcc, s[72:73], s[68:69]
	v_cndmask_b32_e32 v66, v66, v18, vcc
	s_and_b64 vcc, vcc, s[64:65]
	v_cndmask_b32_e32 v65, v65, v18, vcc
	s_and_b64 vcc, vcc, s[60:61]
	v_cndmask_b32_e32 v64, v64, v18, vcc
	s_and_b64 vcc, vcc, s[56:57]
	v_cndmask_b32_e32 v63, v63, v18, vcc
	s_and_b64 vcc, vcc, s[52:53]
	v_cndmask_b32_e32 v62, v62, v18, vcc
	s_and_b64 vcc, vcc, s[48:49]
	v_cndmask_b32_e32 v61, v61, v18, vcc
	s_and_b64 vcc, vcc, s[44:45]
	v_cndmask_b32_e32 v60, v60, v18, vcc
	s_and_b64 vcc, vcc, s[40:41]
	v_cndmask_b32_e32 v59, v59, v18, vcc
	s_and_b64 vcc, vcc, s[36:37]
	v_cndmask_b32_e32 v58, v58, v18, vcc
	s_and_b64 vcc, vcc, s[30:31]
	v_cndmask_b32_e32 v57, v57, v18, vcc
	s_and_b64 vcc, vcc, s[26:27]
	v_cndmask_b32_e32 v56, v56, v18, vcc
	s_and_b64 vcc, vcc, s[22:23]
	v_cndmask_b32_e32 v55, v55, v18, vcc
	s_and_b64 vcc, vcc, s[18:19]
	v_cndmask_b32_e32 v54, v54, v18, vcc
	s_and_b64 vcc, vcc, s[14:15]
	v_cndmask_b32_e32 v53, v53, v18, vcc
	s_and_b64 vcc, vcc, s[10:11]
	v_cndmask_b32_e32 v52, v52, v18, vcc
	v_max_f32_e32 v3, v68, v68
	v_max_f32_e32 v4, v52, v52
	v_max_f32_e32 v3, v3, v4
	v_max3_f32 v4, v53, v70, v54
	v_max3_f32 v3, v3, v69, v71
	v_max3_f32 v4, v4, v72, v56
	v_max3_f32 v3, v3, v55, v73
	v_max3_f32 v4, v4, v74, v58
	v_max3_f32 v3, v3, v57, v75
	v_max3_f32 v4, v4, v76, v60
	v_max3_f32 v3, v3, v59, v77
	v_max3_f32 v4, v4, v78, v62
	v_max3_f32 v3, v3, v61, v79
	v_cndmask_b32_e64 v83, v83, v18, s[70:71]
	v_max3_f32 v4, v4, v80, v64
	v_max3_f32 v3, v3, v63, v81
	v_cndmask_b32_e64 v67, v67, v18, s[72:73]
	v_max3_f32 v4, v4, v82, v66
	v_max3_f32 v3, v3, v65, v83
	v_max3_f32 v3, v3, v67, v4
	v_mov_b32_e32 v4, v3
	s_nop 1
	v_permlane32_swap_b32_e32 v3, v4
	v_max_f32_e32 v4, v4, v4
	v_max_f32_e32 v3, v3, v3
	v_max_f32_e32 v84, v3, v4
	v_add_f32_e32 v191, v193, v84
	v_cvt_pk_bf16_f32 v3, v191, 0
	v_lshlrev_b32_e32 v3, 16, v3
	v_sub_f32_e32 v4, v191, v3
	v_cvt_pk_bf16_f32 v85, v4, 0
	v_lshlrev_b32_e32 v85, 16, v85
	v_sub_f32_e32 v4, v4, v85
	v_cvt_pk_bf16_f32 v3, 1.0, v3
; #define LAS __attribute__((address_space(3)))
; __device__ __forceinline__ unsigned cvtpk(float lo, float hi) { f32x2 v = {lo, hi}; bf16x2_t b = __builtin_convertvector(v, bf16x2_t); return __builtin_bit_cast(unsigned, b); }
; __device__ __forceinline__ float fadd_s(float a, float b) { float r = a + b; asm volatile("" : "+v"(r)); return r; }
; #define ATT_LDS_WAIT() asm volatile("s_waitcnt lgkmcnt(0)" ::: "memory")
; #define ATT_PACK4(P, B, F) (u32x4){F(P[B], P[B + 1]), F(P[B + 2], P[B + 3]), F(P[B + 4], P[B + 5]), F(P[B + 6], P[B + 7])}
;     bf16x8 kf[8]; kfrags(kf, kslot, r32, hi);
;     f32x16 p0, p1;
; #pragma unroll
;     for (int g = 0; g < 4; ++g) { const f32x4 c0 = ld4(ckt + 8 * g), c1 = ld4(ckt + 32 + 8 * g);
; #pragma unroll
;         for (int i = 0; i < 4; ++i) { p0[4 * g + i] = c0[i]; p1[4 * g + i] = c1[i]; } }
;     u32x4 kn = {0u, 0xBF800000u, 0xBF80BF80u, 0u}; if (hi) { kn.y = 0u; kn.z = 0u; }
;     const bf16x8 kneg = __builtin_bit_cast(bf16x8, kn);
;     p0 = __builtin_amdgcn_mfma_f32_32x32x16_bf16(kneg, st.mq, p0, 0, 0, 0);
;     p1 = __builtin_amdgcn_mfma_f32_32x32x16_bf16(kneg, st.mq, p1, 0, 0, 0);
;     ...
;         for (int r = 0; r < 16; ++r) { p0[r] -= dl; p1[r] -= dl; }
;         if (!first) {
;             const float f = __builtin_amdgcn_exp2f(-dl);
;             st.l *= f;
;             if (hi == 0) wsf[r32] = f;
;             ATT_LDS_WAIT();
; #pragma unroll
;             for (int g = 0; g < 4; ++g) { const f32x4 fv = *(const LAS f32x4*)(wsf + 8 * g + 4 * hi);
; #pragma unroll
;                 for (int i = 0; i < 4; ++i) { st.o[0][4 * g + i] *= fv[i]; st.o[1][4 * g + i] *= fv[i]; } }
;         }
;     }
;     __builtin_amdgcn_sched_barrier(0);
;     VFrags vf; vfrags(vf, vp);
;     float sacc = 0.f, sacc2 = 0.f;
; #pragma unroll
;     for (int r = 0; r < 16; ++r) { p0[r] = __builtin_amdgcn_exp2f(p0[r]); p1[r] = __builtin_amdgcn_exp2f(p1[r]); sacc = fadd_s(sacc, p0[r]); sacc2 = fadd_s(sacc2, p1[r]); }
;     st.l = fadd_s(st.l, fadd_s(sacc, sacc2));
;     const u32x4 pw0 = ATT_PACK4(p0, 0, cvtpk), pw1 = ATT_PACK4(p0, 8, cvtpk), pw2 = ATT_PACK4(p1, 0, cvtpk), pw3 = ATT_PACK4(p1, 8, cvtpk);
;     __builtin_amdgcn_sched_barrier(0);
;     ...
;     pv(st.o, vf, pw0, pw1, pw2, pw3);
	v_cvt_pk_bf16_f32 v4, v85, v4
	v_cndmask_b32_e64 v4, 0, v4, s[6:7]
	v_cndmask_b32_e64 v3, 0, v3, s[6:7]
	v_sub_f32_e32 v68, v68, v84
	v_sub_f32_e32 v112, v52, v84
	v_sub_f32_e32 v69, v69, v84
	v_sub_f32_e32 v113, v53, v84
	v_sub_f32_e32 v70, v70, v84
	v_sub_f32_e32 v114, v54, v84
	v_sub_f32_e32 v71, v71, v84
	v_sub_f32_e32 v115, v55, v84
	v_sub_f32_e32 v72, v72, v84
	v_sub_f32_e32 v56, v56, v84
	v_sub_f32_e32 v73, v73, v84
	v_sub_f32_e32 v57, v57, v84
	v_sub_f32_e32 v74, v74, v84
	v_sub_f32_e32 v58, v58, v84
	v_sub_f32_e32 v75, v75, v84
	v_sub_f32_e32 v59, v59, v84
	v_sub_f32_e32 v76, v76, v84
	v_sub_f32_e32 v60, v60, v84
	v_sub_f32_e32 v77, v77, v84
	v_sub_f32_e32 v61, v61, v84
	v_sub_f32_e32 v78, v78, v84
	v_sub_f32_e32 v62, v62, v84
	v_sub_f32_e32 v79, v79, v84
	v_sub_f32_e32 v63, v63, v84
	v_sub_f32_e32 v80, v80, v84
	v_sub_f32_e32 v64, v64, v84
	v_sub_f32_e32 v81, v81, v84
	v_sub_f32_e32 v65, v65, v84
	v_sub_f32_e32 v82, v82, v84
	v_sub_f32_e32 v66, v66, v84
	v_sub_f32_e32 v83, v83, v84
	v_sub_f32_e32 v67, v67, v84
	v_exp_f32_e32 v68, v68
	v_exp_f32_e32 v164, v112
	v_exp_f32_e32 v69, v69
	v_exp_f32_e32 v165, v113
	v_add_f32_e32 v112, 0, v68
	v_exp_f32_e32 v70, v70
	ds_read_b64_tr_b16 v[52:53], v190 offset:57344
	ds_read_b64_tr_b16 v[54:55], v190 offset:57856
	ds_read_b64_tr_b16 v[84:85], v190 offset:58368
	ds_read_b64_tr_b16 v[86:87], v190 offset:58880
	ds_read_b64_tr_b16 v[88:89], v190 offset:59392
	ds_read_b64_tr_b16 v[90:91], v190 offset:59904
	ds_read_b64_tr_b16 v[92:93], v190 offset:60416
	ds_read_b64_tr_b16 v[94:95], v190 offset:60928
	ds_read_b64_tr_b16 v[96:97], v190 offset:61440
	ds_read_b64_tr_b16 v[98:99], v190 offset:61952
	ds_read_b64_tr_b16 v[100:101], v190 offset:62464
	ds_read_b64_tr_b16 v[102:103], v190 offset:62976
	ds_read_b64_tr_b16 v[104:105], v190 offset:63488
	ds_read_b64_tr_b16 v[106:107], v190 offset:64000
	ds_read_b64_tr_b16 v[108:109], v190 offset:64512
	ds_read_b64_tr_b16 v[110:111], v190 offset:65024
	v_exp_f32_e32 v166, v114
	v_add_f32_e32 v160, 0, v164
	v_add_f32_e32 v112, v112, v69
	v_exp_f32_e32 v71, v71
	v_exp_f32_e32 v167, v115
	v_add_f32_e32 v113, v160, v165
	v_add_f32_e32 v112, v112, v70
	v_exp_f32_e32 v72, v72
	v_add_f32_e32 v113, v113, v166
	v_exp_f32_e32 v56, v56
	v_add_f32_e32 v112, v112, v71
	v_exp_f32_e32 v73, v73
	v_add_f32_e32 v113, v113, v167
	v_exp_f32_e32 v57, v57
	v_add_f32_e32 v112, v112, v72
	v_exp_f32_e32 v74, v74
	v_add_f32_e32 v113, v113, v56
	v_exp_f32_e32 v58, v58
	v_add_f32_e32 v112, v112, v73
	v_exp_f32_e32 v75, v75
	v_add_f32_e32 v113, v113, v57
	v_exp_f32_e32 v59, v59
	v_add_f32_e32 v112, v112, v74
	v_exp_f32_e32 v76, v76
	v_add_f32_e32 v113, v113, v58
	v_exp_f32_e32 v60, v60
	v_add_f32_e32 v112, v112, v75
	v_exp_f32_e32 v77, v77
	v_add_f32_e32 v113, v113, v59
	v_exp_f32_e32 v61, v61
	v_add_f32_e32 v112, v76, v112
	v_exp_f32_e32 v78, v78
	v_add_f32_e32 v113, v60, v113
	v_exp_f32_e32 v62, v62
	v_add_f32_e32 v112, v77, v112
	v_exp_f32_e32 v79, v79
	v_add_f32_e32 v113, v61, v113
	v_exp_f32_e32 v63, v63
	v_add_f32_e32 v112, v78, v112
	v_exp_f32_e32 v80, v80
	v_add_f32_e32 v113, v62, v113
	v_exp_f32_e32 v64, v64
	v_add_f32_e32 v112, v79, v112
	v_exp_f32_e32 v81, v81
	v_add_f32_e32 v113, v63, v113
	v_exp_f32_e32 v65, v65
	v_add_f32_e32 v112, v80, v112
	v_exp_f32_e32 v82, v82
	v_add_f32_e32 v113, v64, v113
	v_exp_f32_e32 v66, v66
	v_add_f32_e32 v112, v81, v112
	v_exp_f32_e32 v83, v83
	v_add_f32_e32 v113, v65, v113
	v_exp_f32_e32 v67, v67
	v_add_f32_e32 v112, v82, v112
	v_add_f32_e32 v113, v66, v113
	v_add_f32_e32 v112, v83, v112
	v_add_f32_e32 v113, v67, v113
	v_cvt_pk_bf16_f32 v114, v72, v73
	v_add_f32_e32 v112, v112, v113
	v_cvt_pk_bf16_f32 v113, v70, v71
	v_add_f32_e32 v194, v192, v112
	v_cvt_pk_bf16_f32 v112, v68, v69
	v_cvt_pk_bf16_f32 v115, v74, v75
	v_cvt_pk_bf16_f32 v160, v76, v77
	v_cvt_pk_bf16_f32 v161, v78, v79
	v_cvt_pk_bf16_f32 v162, v80, v81
	v_cvt_pk_bf16_f32 v163, v82, v83
	v_cvt_pk_bf16_f32 v164, v164, v165
	v_cvt_pk_bf16_f32 v165, v166, v167
	v_cvt_pk_bf16_f32 v166, v56, v57
	v_cvt_pk_bf16_f32 v167, v58, v59
	v_cvt_pk_bf16_f32 v198, v60, v61
	v_cvt_pk_bf16_f32 v199, v62, v63
	v_cvt_pk_bf16_f32 v200, v64, v65
	v_cvt_pk_bf16_f32 v201, v66, v67
	s_waitcnt lgkmcnt(14)
	v_mfma_f32_32x32x16_bf16 v[68:83], v[112:115], v[52:55], v[20:35]
	s_waitcnt lgkmcnt(6)
	v_mfma_f32_32x32x16_bf16 v[52:67], v[112:115], v[96:99], v[36:51]
	v_mfma_f32_32x32x16_bf16 v[68:83], v[160:163], v[84:87], v[68:83]
	s_waitcnt lgkmcnt(4)
	v_mfma_f32_32x32x16_bf16 v[52:67], v[160:163], v[100:103], v[52:67]
	v_mfma_f32_32x32x16_bf16 v[68:83], v[164:167], v[88:91], v[68:83]
	s_waitcnt lgkmcnt(2)
	v_mfma_f32_32x32x16_bf16 v[52:67], v[164:167], v[104:107], v[52:67]
	v_mfma_f32_32x32x16_bf16 v[68:83], v[198:201], v[92:95], v[68:83]
	ds_read_b128 v[84:87], v196
	ds_read_b128 v[88:91], v196 offset:32
	ds_read_b128 v[92:95], v196 offset:64
	ds_read_b128 v[96:99], v196 offset:96
	s_waitcnt lgkmcnt(4)
	v_mfma_f32_32x32x16_bf16 v[52:67], v[198:201], v[108:111], v[52:67]
	ds_read_b128 v[100:103], v196 offset:128
	ds_read_b128 v[104:107], v196 offset:160
	ds_read_b128 v[108:111], v196 offset:192
	ds_read_b128 v[112:115], v196 offset:224
	ds_read_b128 v[160:163], v195
	ds_read_b128 v[164:167], v195 offset:512
	s_waitcnt lgkmcnt(6)
; #define LAS __attribute__((address_space(3)))
; __device__ __forceinline__ int crow(int r, int hi) { return (r & 3) + 8 * (r >> 2) + 4 * hi; }
; __device__ __forceinline__ float swap_max(float m) { auto rr = __builtin_amdgcn_permlane32_swap(__float_as_uint(m), __float_as_uint(m), false, false); return fmaxf(__uint_as_float(rr[0]), __uint_as_float(rr[1])); }
; __device__ __forceinline__ float max3f(float a, float b, float c) { return __builtin_fmaxf(__builtin_fmaxf(a, b), c); }
; #define ATT_LDS_WAIT() asm volatile("s_waitcnt lgkmcnt(0)" ::: "memory")
;     ...
;     for (int d0 = 0; d0 < 4; ++d0) {
;         p0 = __builtin_amdgcn_mfma_f32_32x32x16_bf16(kf[2 * d0], qr[d0], p0, 0, 0, 0);
;         p1 = __builtin_amdgcn_mfma_f32_32x32x16_bf16(kf[2 * d0 + 1], qr[d0], p1, 0, 0, 0);
;     }
;     __builtin_amdgcn_sched_barrier(0);
;     if (LEVEL == 2) { asm volatile("" :: "v"(p0), "v"(p1)); return; }
;     if (masked) {
;         asm volatile("; masked tile" ::: "memory");
; #pragma unroll
;         for (int r = 0; r < 16; ++r) { const int kv = crow(r, hi); if (kv >= qlim) p0[r] = NEG; if (kv + 32 >= qlim) p1[r] = NEG; }
;     }
;     float rm = max3f(p0[0], p1[0], p0[1]), rm2 = max3f(p1[1], p0[2], p1[2]);
; #pragma unroll
;     for (int r = 3; r < 15; r += 2) { rm = max3f(rm, p0[r], p1[r]); rm2 = max3f(rm2, p0[r + 1], p1[r + 1]); }
;     rm = max3f(rm, p0[15], p1[15]); rm = swap_max(max3f(rm, rm2, rm2));
;     if (first || __any(rm > FOX_THR)) {
;         const float dl = first ? rm : fmaxf(rm, 0.f);
;         st.m += dl; st.mq = make_mq(st.m, hi);
; #pragma unroll
;         for (int r = 0; r < 16; ++r) { p0[r] -= dl; p1[r] -= dl; }
;         if (!first) {
;             const float f = __builtin_amdgcn_exp2f(-dl);
;             st.l *= f;
;             if (hi == 0) wsf[r32] = f;
;             ATT_LDS_WAIT();
; #pragma unroll
;             for (int g = 0; g < 4; ++g) { const f32x4 fv = *(const LAS f32x4*)(wsf + 8 * g + 4 * hi);
; #pragma unroll
;                 for (int i = 0; i < 4; ++i) { st.o[0][4 * g + i] *= fv[i]; st.o[1][4 * g + i] *= fv[i]; } }
;         }
	v_mfma_f32_32x32x16_bf16 v[84:99], v[120:123], v[2:5], v[84:99]
	s_waitcnt lgkmcnt(2)
	v_mfma_f32_32x32x16_bf16 v[100:115], v[120:123], v[2:5], v[100:115]
	s_waitcnt lgkmcnt(1)
	v_mfma_f32_32x32x16_bf16 v[84:99], v[160:163], v[6:9], v[84:99]
	s_waitcnt lgkmcnt(0)
	v_mfma_f32_32x32x16_bf16 v[100:115], v[164:167], v[6:9], v[100:115]
	ds_read_b128 v[160:163], v195 offset:2048
	ds_read_b128 v[164:167], v195 offset:2560
	s_waitcnt lgkmcnt(1)
	v_mfma_f32_32x32x16_bf16 v[84:99], v[160:163], v[10:13], v[84:99]
	s_waitcnt lgkmcnt(0)
	v_mfma_f32_32x32x16_bf16 v[100:115], v[164:167], v[10:13], v[100:115]
	ds_read_b128 v[160:163], v195 offset:4096
	ds_read_b128 v[164:167], v195 offset:4608
	s_waitcnt lgkmcnt(1)
	v_mfma_f32_32x32x16_bf16 v[84:99], v[160:163], v[14:17], v[84:99]
	s_waitcnt lgkmcnt(0)
	v_mfma_f32_32x32x16_bf16 v[100:115], v[164:167], v[14:17], v[100:115]
	ds_read_b128 v[160:163], v195 offset:6144
	ds_read_b128 v[164:167], v195 offset:6656
	s_waitcnt lgkmcnt(1)
	v_mfma_f32_32x32x16_bf16 v[84:99], v[160:163], v[116:119], v[84:99]
	s_waitcnt lgkmcnt(0)
	v_mfma_f32_32x32x16_bf16 v[100:115], v[164:167], v[116:119], v[100:115]
	s_nop 11
	v_max_f32_e32 v160, v100, v100
	v_max_f32_e32 v161, v84, v84
	v_max_f32_e32 v160, v161, v160
	v_max3_f32 v161, v101, v86, v102
	v_max3_f32 v160, v160, v85, v87
	v_max3_f32 v161, v161, v88, v104
	v_max3_f32 v160, v160, v103, v89
	v_max3_f32 v161, v161, v90, v106
	v_max3_f32 v160, v160, v105, v91
	v_max3_f32 v161, v161, v92, v108
	v_max3_f32 v160, v160, v107, v93
	v_max3_f32 v161, v161, v94, v110
	v_max3_f32 v160, v160, v109, v95
	v_max3_f32 v161, v161, v96, v112
	v_max3_f32 v160, v160, v111, v97
	v_max3_f32 v161, v161, v98, v114
	v_max3_f32 v160, v160, v113, v99
	v_max3_f32 v160, v160, v115, v161
	v_mov_b32_e32 v161, v160
	s_nop 1
	v_permlane32_swap_b32_e32 v160, v161
	v_max_f32_e32 v161, v161, v161
	v_max_f32_e32 v160, v160, v160
	v_max_f32_e32 v160, v160, v161
	s_mov_b32 s3, 0x41000000
	v_cmp_lt_f32_e32 vcc, s3, v160
	s_cbranch_vccz .LBB0_324
	v_max_f32_e32 v160, 0, v160
	v_exp_f32_e64 v161, -v160
	s_and_saveexec_b64 s[4:5], s[6:7]
	ds_write_b32 v182, v161
	s_or_b64 exec, exec, s[4:5]
	v_add_f32_e32 v191, v191, v160
	v_cvt_pk_bf16_f32 v3, v191, 0
	v_lshlrev_b32_e32 v3, 16, v3
	v_sub_f32_e32 v4, v191, v3
	v_cvt_pk_bf16_f32 v162, v4, 0
	v_lshlrev_b32_e32 v162, 16, v162
	v_sub_f32_e32 v4, v4, v162
	s_waitcnt lgkmcnt(0)
	v_add_u32_e32 v197, s78, v172
	v_cvt_pk_bf16_f32 v4, v162, v4
	v_pk_add_f32 v[84:85], v[84:85], v[160:161] op_sel_hi:[1,0] neg_lo:[0,1] neg_hi:[0,1]
	v_pk_add_f32 v[100:101], v[100:101], v[160:161] op_sel_hi:[1,0] neg_lo:[0,1] neg_hi:[0,1]
	v_pk_add_f32 v[86:87], v[86:87], v[160:161] op_sel_hi:[1,0] neg_lo:[0,1] neg_hi:[0,1]
	v_pk_add_f32 v[102:103], v[102:103], v[160:161] op_sel_hi:[1,0] neg_lo:[0,1] neg_hi:[0,1]
	v_pk_add_f32 v[88:89], v[88:89], v[160:161] op_sel_hi:[1,0] neg_lo:[0,1] neg_hi:[0,1]
	v_pk_add_f32 v[104:105], v[104:105], v[160:161] op_sel_hi:[1,0] neg_lo:[0,1] neg_hi:[0,1]
	v_pk_add_f32 v[90:91], v[90:91], v[160:161] op_sel_hi:[1,0] neg_lo:[0,1] neg_hi:[0,1]
	v_pk_add_f32 v[106:107], v[106:107], v[160:161] op_sel_hi:[1,0] neg_lo:[0,1] neg_hi:[0,1]
	v_pk_add_f32 v[92:93], v[92:93], v[160:161] op_sel_hi:[1,0] neg_lo:[0,1] neg_hi:[0,1]
	v_pk_add_f32 v[108:109], v[108:109], v[160:161] op_sel_hi:[1,0] neg_lo:[0,1] neg_hi:[0,1]
	v_pk_add_f32 v[94:95], v[94:95], v[160:161] op_sel_hi:[1,0] neg_lo:[0,1] neg_hi:[0,1]
	v_pk_add_f32 v[110:111], v[110:111], v[160:161] op_sel_hi:[1,0] neg_lo:[0,1] neg_hi:[0,1]
	v_pk_add_f32 v[96:97], v[96:97], v[160:161] op_sel_hi:[1,0] neg_lo:[0,1] neg_hi:[0,1]
	v_pk_add_f32 v[112:113], v[112:113], v[160:161] op_sel_hi:[1,0] neg_lo:[0,1] neg_hi:[0,1]
	v_pk_add_f32 v[98:99], v[98:99], v[160:161] op_sel_hi:[1,0] neg_lo:[0,1] neg_hi:[0,1]
	v_pk_add_f32 v[114:115], v[114:115], v[160:161] op_sel_hi:[1,0] neg_lo:[0,1] neg_hi:[0,1]
	v_mul_f32_e32 v194, v194, v161
	ds_read_b128 v[160:163], v197
	ds_read_b128 v[164:167], v197 offset:32
	ds_read_b128 v[198:201], v197 offset:64
	ds_read_b128 v[202:205], v197 offset:96
	v_cvt_pk_bf16_f32 v3, 1.0, v3
	v_cndmask_b32_e64 v4, 0, v4, s[6:7]
	v_cndmask_b32_e64 v3, 0, v3, s[6:7]
	s_waitcnt lgkmcnt(1)
	v_pk_mul_f32 v[76:77], v[76:77], v[198:199]
	s_waitcnt lgkmcnt(0)
	v_pk_mul_f32 v[80:81], v[80:81], v[202:203]
	v_pk_mul_f32 v[72:73], v[72:73], v[164:165]
	v_pk_mul_f32 v[82:83], v[82:83], v[204:205]
	v_pk_mul_f32 v[78:79], v[78:79], v[200:201]
	v_pk_mul_f32 v[74:75], v[74:75], v[166:167]
	v_pk_mul_f32 v[70:71], v[70:71], v[162:163]
	v_pk_mul_f32 v[68:69], v[68:69], v[160:161]
	v_pk_mul_f32 v[64:65], v[64:65], v[202:203]
	v_pk_mul_f32 v[60:61], v[60:61], v[198:199]
	v_pk_mul_f32 v[56:57], v[56:57], v[164:165]
	v_pk_mul_f32 v[66:67], v[66:67], v[204:205]
	v_pk_mul_f32 v[62:63], v[62:63], v[200:201]
	v_pk_mul_f32 v[58:59], v[58:59], v[166:167]
	v_pk_mul_f32 v[54:55], v[54:55], v[162:163]
	v_pk_mul_f32 v[52:53], v[52:53], v[160:161]

; __device__ __forceinline__ void fox_pair_pv(FoxState& st, const PairP& pp, lds_cptr vpB) {
;     { VFrags vf; vfrags(vf, vpB + 8192); pv(st.o, vf, pp.w[0], pp.w[1], pp.w[2], pp.w[3]); }
;     { VFrags vf; vfrags(vf, vpB); pv(st.o, vf, pp.w[4], pp.w[5], pp.w[6], pp.w[7]); }
; }
; __device__ __forceinline__ void prompt_unit_fox(const Args& a, int l, int b, int h, int qb, LAS unsigned char* lds) {
;     ...
;         slot = (slot == 2) ? 0 : slot + 1;
;     }
;     ...
;     if (pending) fox_pair_pv(st, pp, vp0 + pslot * 16384);
.LBB0_345:
.LBB0_346:
	s_add_i32 s3, s75, 1
	s_cmp_lg_u32 s75, 2
	s_cselect_b32 s75, s3, 0
	s_add_i32 s3, s90, -1
	s_cmp_lt_i32 s90, 1
	s_cbranch_scc1 .LBB0_348
	v_mov_b64_e32 v[156:157], v[160:161]
	s_mov_b32 s90, s3
	v_mov_b64_e32 v[158:159], v[162:163]
	v_mov_b32_e32 v192, v194
	v_mov_b32_e32 v193, v191
	s_branch .LBB0_312
.LBB0_348:
	s_nop 11
	v_mov_b64_e32 v[68:69], v[20:21]
	v_mov_b64_e32 v[70:71], v[22:23]
	v_mov_b64_e32 v[72:73], v[24:25]
	v_mov_b64_e32 v[74:75], v[26:27]
	v_mov_b64_e32 v[76:77], v[28:29]
	v_mov_b64_e32 v[78:79], v[30:31]
	v_mov_b64_e32 v[80:81], v[32:33]
	v_mov_b64_e32 v[82:83], v[34:35]
	v_mov_b64_e32 v[52:53], v[36:37]
	v_mov_b64_e32 v[54:55], v[38:39]
	v_mov_b64_e32 v[56:57], v[40:41]
	v_mov_b64_e32 v[58:59], v[42:43]
	v_mov_b64_e32 v[60:61], v[44:45]
	v_mov_b64_e32 v[62:63], v[46:47]
	v_mov_b64_e32 v[64:65], v[48:49]
	v_mov_b64_e32 v[66:67], v[50:51]
	s_and_b64 vcc, exec, s[4:5]
	s_cbranch_vccz .LBB0_350
	v_lshl_add_u32 v2, s1, 14, v180
	ds_read_b64_tr_b16 v[6:7], v2 offset:57344
	ds_read_b64_tr_b16 v[8:9], v2 offset:57856
	ds_read_b64_tr_b16 v[10:11], v2 offset:58368
	ds_read_b64_tr_b16 v[12:13], v2 offset:58880
	s_waitcnt lgkmcnt(2)
	v_mfma_f32_32x32x16_bf16 v[68:83], v[152:155], v[6:9], v[68:83]
	ds_read_b64_tr_b16 v[6:7], v2 offset:61440
	ds_read_b64_tr_b16 v[8:9], v2 offset:61952
	ds_read_b64_tr_b16 v[14:15], v2 offset:62464
	ds_read_b64_tr_b16 v[16:17], v2 offset:62976
	s_waitcnt lgkmcnt(2)
	v_mfma_f32_32x32x16_bf16 v[52:67], v[152:155], v[6:9], v[52:67]
	v_mfma_f32_32x32x16_bf16 v[68:83], v[148:151], v[10:13], v[68:83]
	ds_read_b64_tr_b16 v[6:7], v2 offset:59392
	ds_read_b64_tr_b16 v[8:9], v2 offset:59904
	ds_read_b64_tr_b16 v[10:11], v2 offset:60416
	ds_read_b64_tr_b16 v[12:13], v2 offset:60928
	s_waitcnt lgkmcnt(4)
	v_mfma_f32_32x32x16_bf16 v[52:67], v[148:151], v[14:17], v[52:67]
	s_waitcnt lgkmcnt(2)
	v_mfma_f32_32x32x16_bf16 v[68:83], v[144:147], v[6:9], v[68:83]
	ds_read_b64_tr_b16 v[6:7], v2 offset:63488
	ds_read_b64_tr_b16 v[8:9], v2 offset:64000
	ds_read_b64_tr_b16 v[14:15], v2 offset:64512
	ds_read_b64_tr_b16 v[16:17], v2 offset:65024
	s_waitcnt lgkmcnt(2)
	v_mfma_f32_32x32x16_bf16 v[52:67], v[144:147], v[6:9], v[52:67]
	v_mfma_f32_32x32x16_bf16 v[68:83], v[140:143], v[10:13], v[68:83]
	ds_read_b64_tr_b16 v[6:7], v2 offset:49152
	ds_read_b64_tr_b16 v[8:9], v2 offset:49664
	ds_read_b64_tr_b16 v[10:11], v2 offset:50176
	ds_read_b64_tr_b16 v[12:13], v2 offset:50688
	s_waitcnt lgkmcnt(4)
	v_mfma_f32_32x32x16_bf16 v[52:67], v[140:143], v[14:17], v[52:67]
	s_waitcnt lgkmcnt(2)
	v_mfma_f32_32x32x16_bf16 v[68:83], v[136:139], v[6:9], v[68:83]
	ds_read_b64_tr_b16 v[6:7], v2 offset:53248
	ds_read_b64_tr_b16 v[8:9], v2 offset:53760
	ds_read_b64_tr_b16 v[14:15], v2 offset:54272
	ds_read_b64_tr_b16 v[16:17], v2 offset:54784
	s_waitcnt lgkmcnt(2)
	v_mfma_f32_32x32x16_bf16 v[52:67], v[136:139], v[6:9], v[52:67]
	v_mfma_f32_32x32x16_bf16 v[68:83], v[132:135], v[10:13], v[68:83]
	ds_read_b64_tr_b16 v[6:7], v2 offset:51200
	ds_read_b64_tr_b16 v[8:9], v2 offset:51712
	ds_read_b64_tr_b16 v[10:11], v2 offset:52224
	ds_read_b64_tr_b16 v[12:13], v2 offset:52736
	s_waitcnt lgkmcnt(4)
	v_mfma_f32_32x32x16_bf16 v[52:67], v[132:135], v[14:17], v[52:67]
	s_waitcnt lgkmcnt(2)
	v_mfma_f32_32x32x16_bf16 v[68:83], v[128:131], v[6:9], v[68:83]
	ds_read_b64_tr_b16 v[6:7], v2 offset:55296
	ds_read_b64_tr_b16 v[8:9], v2 offset:55808
	ds_read_b64_tr_b16 v[14:15], v2 offset:56320
	ds_read_b64_tr_b16 v[16:17], v2 offset:56832
	s_waitcnt lgkmcnt(2)
	v_mfma_f32_32x32x16_bf16 v[52:67], v[128:131], v[6:9], v[52:67]
	v_mfma_f32_32x32x16_bf16 v[68:83], v[124:127], v[10:13], v[68:83]
	s_waitcnt lgkmcnt(0)
	v_mfma_f32_32x32x16_bf16 v[52:67], v[124:127], v[14:17], v[52:67]

; #define ATT_WAIT_BAR() asm volatile("s_waitcnt vmcnt(0) lgkmcnt(0)\n\ts_barrier" ::: "memory")
; __device__ __forceinline__ void prompt_unit_fox(const Args& a, int l, int b, int h, int qb, LAS unsigned char* lds) {
;     ...
;         ATT_WAIT_BAR();
;         if (jp >= 1) ATT_DMA2(jp - 1, slot == 2 ? 0 : slot + 1);
.Lfox_top_l1:
	s_cmp_lg_u32 s78, 0
	s_cbranch_scc0 .LBB0_995
	s_add_i32 s80, s78, -1
	s_mov_b32 s81, s87
	s_lshl_b32 s33, s93, 14
	s_lshl_b64 s[80:81], s[80:81], 18
	s_add_i32 s76, s33, 0x4000
	s_cmp_lg_u32 s93, 2
	s_cselect_b32 s76, s76, 0
	v_lshl_add_u64 v[244:245], v[170:171], 0, s[80:81]
	s_add_i32 s77, s96, s76
	s_mov_b32 m0, s77
	s_nop 0
	global_load_lds_dwordx4 v[244:245], off
	s_mov_b64 vcc, 0x20000
	v_lshl_add_u64 v[244:245], v[244:245], 0, vcc
	s_add_i32 s77, s97, s76
	s_mov_b32 m0, s77
	s_nop 0
	global_load_lds_dwordx4 v[244:245], off
	v_lshl_add_u64 v[244:245], v[172:173], 0, s[80:81]
	s_add_i32 s77, s84, s76
	s_mov_b32 m0, s77
	s_nop 0
	global_load_lds_dwordx4 v[244:245], off
	v_lshl_add_u64 v[244:245], v[244:245], 0, vcc
	s_add_i32 s76, s85, s76
	s_mov_b32 m0, s76
	s_nop 0
	global_load_lds_dwordx4 v[244:245], off
	s_cbranch_execnz .LBB0_967

; __device__ __forceinline__ int crow(int r, int hi) { return (r & 3) + 8 * (r >> 2) + 4 * hi; }
; __device__ __forceinline__ float swap_max(float m) { auto rr = __builtin_amdgcn_permlane32_swap(__float_as_uint(m), __float_as_uint(m), false, false); return fmaxf(__uint_as_float(rr[0]), __uint_as_float(rr[1])); }
; __device__ __forceinline__ float max3f(float a, float b, float c) { return __builtin_fmaxf(__builtin_fmaxf(a, b), c); }
;     bf16x8 kf[8]; kfrags(kf, kslot, r32, hi);
;     f32x16 p0, p1;
; #pragma unroll
;     for (int g = 0; g < 4; ++g) { const f32x4 c0 = ld4(ckt + 8 * g), c1 = ld4(ckt + 32 + 8 * g);
; #pragma unroll
;         for (int i = 0; i < 4; ++i) { p0[4 * g + i] = c0[i]; p1[4 * g + i] = c1[i]; } }
;     u32x4 kn = {0u, 0xBF800000u, 0xBF80BF80u, 0u}; if (hi) { kn.y = 0u; kn.z = 0u; }
;     const bf16x8 kneg = __builtin_bit_cast(bf16x8, kn);
;     p0 = __builtin_amdgcn_mfma_f32_32x32x16_bf16(kneg, st.mq, p0, 0, 0, 0);
;     p1 = __builtin_amdgcn_mfma_f32_32x32x16_bf16(kneg, st.mq, p1, 0, 0, 0);
; #pragma unroll
;     for (int d0 = 0; d0 < 4; ++d0) {
;         p0 = __builtin_amdgcn_mfma_f32_32x32x16_bf16(kf[2 * d0], qr[d0], p0, 0, 0, 0);
;         p1 = __builtin_amdgcn_mfma_f32_32x32x16_bf16(kf[2 * d0 + 1], qr[d0], p1, 0, 0, 0);
;     }
;     __builtin_amdgcn_sched_barrier(0);
;     if (LEVEL == 2) { asm volatile("" :: "v"(p0), "v"(p1)); return; }
;     if (masked) {
;         asm volatile("; masked tile" ::: "memory");
; #pragma unroll
;         for (int r = 0; r < 16; ++r) { const int kv = crow(r, hi); if (kv >= qlim) p0[r] = NEG; if (kv + 32 >= qlim) p1[r] = NEG; }
;     }
;     float rm = max3f(p0[0], p1[0], p0[1]), rm2 = max3f(p1[1], p0[2], p1[2]);
; #pragma unroll
;     for (int r = 3; r < 15; r += 2) { rm = max3f(rm, p0[r], p1[r]); rm2 = max3f(rm2, p0[r + 1], p1[r + 1]); }
;     rm = max3f(rm, p0[15], p1[15]); rm = swap_max(max3f(rm, rm2, rm2));
;     if (first || __any(rm > FOX_THR)) {
;         const float dl = first ? rm : fmaxf(rm, 0.f);
;         st.m += dl; st.mq = make_mq(st.m, hi);
; #pragma unroll
;         for (int r = 0; r < 16; ++r) { p0[r] -= dl; p1[r] -= dl; }
.LBB0_969:
	s_add_i32 s80, s33, 0
	s_lshl_b32 s81, s78, 7
	v_add_u32_e32 v190, s33, v175
	s_cmp_ge_i32 s78, s0
	s_mov_b64 s[2:3], -1
	s_cbranch_scc0 .LBB0_980
	s_nop 11
	v_mov_b64_e32 v[66:67], v[50:51]
	v_mov_b64_e32 v[82:83], v[34:35]
	v_mov_b64_e32 v[162:163], v[158:159]
	s_cmp_lg_u32 s78, s0
	v_mov_b64_e32 v[64:65], v[48:49]
	v_mov_b64_e32 v[62:63], v[46:47]
	v_mov_b64_e32 v[60:61], v[44:45]
	v_mov_b64_e32 v[58:59], v[42:43]
	v_mov_b64_e32 v[56:57], v[40:41]
	v_mov_b64_e32 v[54:55], v[38:39]
	v_mov_b64_e32 v[52:53], v[36:37]
	v_mov_b64_e32 v[80:81], v[32:33]
	v_mov_b64_e32 v[78:79], v[30:31]
	v_mov_b64_e32 v[76:77], v[28:29]
	v_mov_b64_e32 v[74:75], v[26:27]
	v_mov_b64_e32 v[72:73], v[24:25]
	v_mov_b64_e32 v[70:71], v[22:23]
	v_mov_b64_e32 v[68:69], v[20:21]
	v_mov_b64_e32 v[160:161], v[156:157]
	v_mov_b32_e32 v194, v192
	v_mov_b32_e32 v191, v193
	s_cbranch_scc1 .LBB0_979
	v_lshl_add_u32 v196, s81, 2, v186
	s_andn2_b64 vcc, exec, s[94:95]
	v_add3_u32 v195, s80, v182, v189
	s_cbranch_vccnz .LBB0_977
	ds_read_b128 v[68:71], v196 offset:256
	ds_read_b128 v[72:75], v196 offset:288
	ds_read_b128 v[76:79], v196 offset:320
	ds_read_b128 v[80:83], v196 offset:352
	ds_read_b128 v[52:55], v196 offset:384
	ds_read_b128 v[56:59], v196 offset:416
	ds_read_b128 v[60:63], v196 offset:448
	ds_read_b128 v[64:67], v196 offset:480
	ds_read_b128 v[84:87], v195 offset:8192
	s_waitcnt lgkmcnt(5)
	v_mfma_f32_32x32x16_bf16 v[68:83], v[120:123], v[156:159], v[68:83]
	s_waitcnt lgkmcnt(0)
	v_mfma_f32_32x32x16_bf16 v[68:83], v[84:87], v[6:9], v[68:83]
	ds_read_b128 v[84:87], v195 offset:8704
	v_mfma_f32_32x32x16_bf16 v[52:67], v[120:123], v[156:159], v[52:67]
	s_waitcnt lgkmcnt(0)
	v_mfma_f32_32x32x16_bf16 v[52:67], v[84:87], v[6:9], v[52:67]
	ds_read_b128 v[84:87], v195 offset:10240
	s_waitcnt lgkmcnt(0)
	v_mfma_f32_32x32x16_bf16 v[68:83], v[84:87], v[10:13], v[68:83]
	ds_read_b128 v[84:87], v195 offset:10752
	s_waitcnt lgkmcnt(0)
	v_mfma_f32_32x32x16_bf16 v[52:67], v[84:87], v[10:13], v[52:67]
	ds_read_b128 v[84:87], v195 offset:12288
	s_waitcnt lgkmcnt(0)
	v_mfma_f32_32x32x16_bf16 v[68:83], v[84:87], v[14:17], v[68:83]
	ds_read_b128 v[84:87], v195 offset:12800
	s_waitcnt lgkmcnt(0)
	v_mfma_f32_32x32x16_bf16 v[52:67], v[84:87], v[14:17], v[52:67]
	ds_read_b128 v[84:87], v195 offset:14336
	s_waitcnt lgkmcnt(0)
	v_mfma_f32_32x32x16_bf16 v[68:83], v[84:87], v[116:119], v[68:83]
	ds_read_b128 v[84:87], v195 offset:14848
	s_waitcnt lgkmcnt(0)
	v_mfma_f32_32x32x16_bf16 v[52:67], v[84:87], v[116:119], v[52:67]
	s_and_b64 vcc, s[70:71], s[66:67]
	s_nop 7
	v_cndmask_b32_e32 v82, v82, v18, vcc
	s_and_b64 vcc, vcc, s[62:63]
	v_cndmask_b32_e32 v81, v81, v18, vcc
	s_and_b64 vcc, vcc, s[58:59]
	v_cndmask_b32_e32 v80, v80, v18, vcc
	s_and_b64 vcc, vcc, s[54:55]
	v_cndmask_b32_e32 v79, v79, v18, vcc
	s_and_b64 vcc, vcc, s[50:51]
	v_cndmask_b32_e32 v78, v78, v18, vcc
	s_and_b64 vcc, vcc, s[46:47]
	v_cndmask_b32_e32 v77, v77, v18, vcc
	s_and_b64 vcc, vcc, s[42:43]
	v_cndmask_b32_e32 v76, v76, v18, vcc
	s_and_b64 vcc, vcc, s[38:39]
	v_cndmask_b32_e32 v75, v75, v18, vcc
	s_and_b64 vcc, vcc, s[34:35]
	v_cndmask_b32_e32 v74, v74, v18, vcc
	s_and_b64 vcc, vcc, s[28:29]
	v_cndmask_b32_e32 v73, v73, v18, vcc
	s_and_b64 vcc, vcc, s[24:25]
	v_cndmask_b32_e64 v3, v68, v18, s[8:9]
	v_cndmask_b32_e32 v72, v72, v18, vcc
	s_and_b64 vcc, vcc, s[20:21]
	v_cndmask_b32_e64 v3, v3, v68, s[12:13]
	v_cndmask_b32_e64 v4, v18, v69, s[12:13]
	v_cndmask_b32_e32 v71, v71, v18, vcc
	s_and_b64 vcc, vcc, s[16:17]
	v_cndmask_b32_e32 v69, v69, v4, vcc
	v_cndmask_b32_e32 v68, v68, v3, vcc
	v_cndmask_b32_e32 v70, v70, v18, vcc
	s_and_b64 vcc, s[72:73], s[68:69]
	v_cndmask_b32_e32 v66, v66, v18, vcc
	s_and_b64 vcc, vcc, s[64:65]
	v_cndmask_b32_e32 v65, v65, v18, vcc
	s_and_b64 vcc, vcc, s[60:61]
	v_cndmask_b32_e32 v64, v64, v18, vcc
	s_and_b64 vcc, vcc, s[56:57]
	v_cndmask_b32_e32 v63, v63, v18, vcc
	s_and_b64 vcc, vcc, s[52:53]
	v_cndmask_b32_e32 v62, v62, v18, vcc
	s_and_b64 vcc, vcc, s[48:49]
	v_cndmask_b32_e32 v61, v61, v18, vcc
	s_and_b64 vcc, vcc, s[44:45]
	v_cndmask_b32_e32 v60, v60, v18, vcc
	s_and_b64 vcc, vcc, s[40:41]
	v_cndmask_b32_e32 v59, v59, v18, vcc
	s_and_b64 vcc, vcc, s[36:37]
	v_cndmask_b32_e32 v58, v58, v18, vcc
	s_and_b64 vcc, vcc, s[30:31]
	v_cndmask_b32_e32 v57, v57, v18, vcc
	s_and_b64 vcc, vcc, s[26:27]
	v_cndmask_b32_e32 v56, v56, v18, vcc
	s_and_b64 vcc, vcc, s[22:23]
	v_cndmask_b32_e32 v55, v55, v18, vcc
	s_and_b64 vcc, vcc, s[18:19]
	v_cndmask_b32_e32 v54, v54, v18, vcc
	s_and_b64 vcc, vcc, s[14:15]
	v_cndmask_b32_e32 v53, v53, v18, vcc
	s_and_b64 vcc, vcc, s[10:11]
	v_cndmask_b32_e32 v52, v52, v18, vcc
	v_max_f32_e32 v3, v68, v68
	v_max_f32_e32 v4, v52, v52
	v_max_f32_e32 v3, v3, v4
	v_max3_f32 v4, v53, v70, v54
	v_max3_f32 v3, v3, v69, v71
	v_max3_f32 v4, v4, v72, v56
	v_max3_f32 v3, v3, v55, v73
	v_max3_f32 v4, v4, v74, v58
	v_max3_f32 v3, v3, v57, v75
	v_max3_f32 v4, v4, v76, v60
	v_max3_f32 v3, v3, v59, v77
	v_max3_f32 v4, v4, v78, v62
	v_max3_f32 v3, v3, v61, v79
	v_cndmask_b32_e64 v83, v83, v18, s[70:71]
	v_max3_f32 v4, v4, v80, v64
	v_max3_f32 v3, v3, v63, v81
	v_cndmask_b32_e64 v67, v67, v18, s[72:73]
	v_max3_f32 v4, v4, v82, v66
	v_max3_f32 v3, v3, v65, v83
	v_max3_f32 v3, v3, v67, v4
	v_mov_b32_e32 v4, v3
	s_nop 1
	v_permlane32_swap_b32_e32 v3, v4
	v_max_f32_e32 v4, v4, v4
	v_max_f32_e32 v3, v3, v3
	v_max_f32_e32 v84, v3, v4
	v_add_f32_e32 v191, v193, v84
	v_cvt_pk_bf16_f32 v3, v191, 0
	v_lshlrev_b32_e32 v3, 16, v3
	v_sub_f32_e32 v4, v191, v3
	v_cvt_pk_bf16_f32 v85, v4, 0
	v_lshlrev_b32_e32 v85, 16, v85
	v_sub_f32_e32 v4, v4, v85
	v_cvt_pk_bf16_f32 v3, 1.0, v3
; #define LAS __attribute__((address_space(3)))
; __device__ __forceinline__ unsigned cvtpk(float lo, float hi) { f32x2 v = {lo, hi}; bf16x2_t b = __builtin_convertvector(v, bf16x2_t); return __builtin_bit_cast(unsigned, b); }
; __device__ __forceinline__ float fadd_s(float a, float b) { float r = a + b; asm volatile("" : "+v"(r)); return r; }
; #define ATT_LDS_WAIT() asm volatile("s_waitcnt lgkmcnt(0)" ::: "memory")
; #define ATT_PACK4(P, B, F) (u32x4){F(P[B], P[B + 1]), F(P[B + 2], P[B + 3]), F(P[B + 4], P[B + 5]), F(P[B + 6], P[B + 7])}
;     bf16x8 kf[8]; kfrags(kf, kslot, r32, hi);
;     f32x16 p0, p1;
; #pragma unroll
;     for (int g = 0; g < 4; ++g) { const f32x4 c0 = ld4(ckt + 8 * g), c1 = ld4(ckt + 32 + 8 * g);
; #pragma unroll
;         for (int i = 0; i < 4; ++i) { p0[4 * g + i] = c0[i]; p1[4 * g + i] = c1[i]; } }
;     u32x4 kn = {0u, 0xBF800000u, 0xBF80BF80u, 0u}; if (hi) { kn.y = 0u; kn.z = 0u; }
;     const bf16x8 kneg = __builtin_bit_cast(bf16x8, kn);
;     p0 = __builtin_amdgcn_mfma_f32_32x32x16_bf16(kneg, st.mq, p0, 0, 0, 0);
;     p1 = __builtin_amdgcn_mfma_f32_32x32x16_bf16(kneg, st.mq, p1, 0, 0, 0);
;     ...
;         for (int r = 0; r < 16; ++r) { p0[r] -= dl; p1[r] -= dl; }
;         if (!first) {
;             const float f = __builtin_amdgcn_exp2f(-dl);
;             st.l *= f;
;             if (hi == 0) wsf[r32] = f;
;             ATT_LDS_WAIT();
; #pragma unroll
;             for (int g = 0; g < 4; ++g) { const f32x4 fv = *(const LAS f32x4*)(wsf + 8 * g + 4 * hi);
; #pragma unroll
;                 for (int i = 0; i < 4; ++i) { st.o[0][4 * g + i] *= fv[i]; st.o[1][4 * g + i] *= fv[i]; } }
;         }
;     }
;     __builtin_amdgcn_sched_barrier(0);
;     VFrags vf; vfrags(vf, vp);
;     float sacc = 0.f, sacc2 = 0.f;
; #pragma unroll
;     for (int r = 0; r < 16; ++r) { p0[r] = __builtin_amdgcn_exp2f(p0[r]); p1[r] = __builtin_amdgcn_exp2f(p1[r]); sacc = fadd_s(sacc, p0[r]); sacc2 = fadd_s(sacc2, p1[r]); }
;     st.l = fadd_s(st.l, fadd_s(sacc, sacc2));
;     const u32x4 pw0 = ATT_PACK4(p0, 0, cvtpk), pw1 = ATT_PACK4(p0, 8, cvtpk), pw2 = ATT_PACK4(p1, 0, cvtpk), pw3 = ATT_PACK4(p1, 8, cvtpk);
;     __builtin_amdgcn_sched_barrier(0);
;     ...
;     pv(st.o, vf, pw0, pw1, pw2, pw3);
	v_cvt_pk_bf16_f32 v4, v85, v4
	v_cndmask_b32_e64 v4, 0, v4, s[6:7]
	v_cndmask_b32_e64 v3, 0, v3, s[6:7]
	v_sub_f32_e32 v68, v68, v84
	v_sub_f32_e32 v112, v52, v84
	v_sub_f32_e32 v69, v69, v84
	v_sub_f32_e32 v113, v53, v84
	v_sub_f32_e32 v70, v70, v84
	v_sub_f32_e32 v114, v54, v84
	v_sub_f32_e32 v71, v71, v84
	v_sub_f32_e32 v115, v55, v84
	v_sub_f32_e32 v72, v72, v84
	v_sub_f32_e32 v56, v56, v84
	v_sub_f32_e32 v73, v73, v84
	v_sub_f32_e32 v57, v57, v84
	v_sub_f32_e32 v74, v74, v84
	v_sub_f32_e32 v58, v58, v84
	v_sub_f32_e32 v75, v75, v84
	v_sub_f32_e32 v59, v59, v84
	v_sub_f32_e32 v76, v76, v84
	v_sub_f32_e32 v60, v60, v84
	v_sub_f32_e32 v77, v77, v84
	v_sub_f32_e32 v61, v61, v84
	v_sub_f32_e32 v78, v78, v84
	v_sub_f32_e32 v62, v62, v84
	v_sub_f32_e32 v79, v79, v84
	v_sub_f32_e32 v63, v63, v84
	v_sub_f32_e32 v80, v80, v84
	v_sub_f32_e32 v64, v64, v84
	v_sub_f32_e32 v81, v81, v84
	v_sub_f32_e32 v65, v65, v84
	v_sub_f32_e32 v82, v82, v84
	v_sub_f32_e32 v66, v66, v84
	v_sub_f32_e32 v83, v83, v84
	v_sub_f32_e32 v67, v67, v84
	v_exp_f32_e32 v68, v68
	v_exp_f32_e32 v164, v112
	v_exp_f32_e32 v69, v69
	v_exp_f32_e32 v165, v113
	v_add_f32_e32 v112, 0, v68
	v_exp_f32_e32 v70, v70
	ds_read_b64_tr_b16 v[52:53], v190 offset:57344
	ds_read_b64_tr_b16 v[54:55], v190 offset:57856
	ds_read_b64_tr_b16 v[84:85], v190 offset:58368
	ds_read_b64_tr_b16 v[86:87], v190 offset:58880
	ds_read_b64_tr_b16 v[88:89], v190 offset:59392
	ds_read_b64_tr_b16 v[90:91], v190 offset:59904
	ds_read_b64_tr_b16 v[92:93], v190 offset:60416
	ds_read_b64_tr_b16 v[94:95], v190 offset:60928
	ds_read_b64_tr_b16 v[96:97], v190 offset:61440
	ds_read_b64_tr_b16 v[98:99], v190 offset:61952
	ds_read_b64_tr_b16 v[100:101], v190 offset:62464
	ds_read_b64_tr_b16 v[102:103], v190 offset:62976
	ds_read_b64_tr_b16 v[104:105], v190 offset:63488
	ds_read_b64_tr_b16 v[106:107], v190 offset:64000
	ds_read_b64_tr_b16 v[108:109], v190 offset:64512
	ds_read_b64_tr_b16 v[110:111], v190 offset:65024
	v_exp_f32_e32 v166, v114
	v_add_f32_e32 v160, 0, v164
	v_add_f32_e32 v112, v112, v69
	v_exp_f32_e32 v71, v71
	v_exp_f32_e32 v167, v115
	v_add_f32_e32 v113, v160, v165
	v_add_f32_e32 v112, v112, v70
	v_exp_f32_e32 v72, v72
	v_add_f32_e32 v113, v113, v166
	v_exp_f32_e32 v56, v56
	v_add_f32_e32 v112, v112, v71
	v_exp_f32_e32 v73, v73
	v_add_f32_e32 v113, v113, v167
	v_exp_f32_e32 v57, v57
	v_add_f32_e32 v112, v112, v72
	v_exp_f32_e32 v74, v74
	v_add_f32_e32 v113, v113, v56
	v_exp_f32_e32 v58, v58
	v_add_f32_e32 v112, v112, v73
	v_exp_f32_e32 v75, v75
	v_add_f32_e32 v113, v113, v57
	v_exp_f32_e32 v59, v59
	v_add_f32_e32 v112, v112, v74
	v_exp_f32_e32 v76, v76
	v_add_f32_e32 v113, v113, v58
	v_exp_f32_e32 v60, v60
	v_add_f32_e32 v112, v112, v75
	v_exp_f32_e32 v77, v77
	v_add_f32_e32 v113, v113, v59
	v_exp_f32_e32 v61, v61
	v_add_f32_e32 v112, v76, v112
	v_exp_f32_e32 v78, v78
	v_add_f32_e32 v113, v60, v113
	v_exp_f32_e32 v62, v62
	v_add_f32_e32 v112, v77, v112
	v_exp_f32_e32 v79, v79
	v_add_f32_e32 v113, v61, v113
	v_exp_f32_e32 v63, v63
	v_add_f32_e32 v112, v78, v112
	v_exp_f32_e32 v80, v80
	v_add_f32_e32 v113, v62, v113
	v_exp_f32_e32 v64, v64
	v_add_f32_e32 v112, v79, v112
	v_exp_f32_e32 v81, v81
	v_add_f32_e32 v113, v63, v113
	v_exp_f32_e32 v65, v65
	v_add_f32_e32 v112, v80, v112
	v_exp_f32_e32 v82, v82
	v_add_f32_e32 v113, v64, v113
	v_exp_f32_e32 v66, v66
	v_add_f32_e32 v112, v81, v112
	v_exp_f32_e32 v83, v83
	v_add_f32_e32 v113, v65, v113
	v_exp_f32_e32 v67, v67
	v_add_f32_e32 v112, v82, v112
	v_add_f32_e32 v113, v66, v113
	v_add_f32_e32 v112, v83, v112
	v_add_f32_e32 v113, v67, v113
	v_cvt_pk_bf16_f32 v114, v72, v73
	v_add_f32_e32 v112, v112, v113
	v_cvt_pk_bf16_f32 v113, v70, v71
	v_add_f32_e32 v194, v192, v112
	v_cvt_pk_bf16_f32 v112, v68, v69
	v_cvt_pk_bf16_f32 v115, v74, v75
	v_cvt_pk_bf16_f32 v160, v76, v77
	v_cvt_pk_bf16_f32 v161, v78, v79
	v_cvt_pk_bf16_f32 v162, v80, v81
	v_cvt_pk_bf16_f32 v163, v82, v83
	v_cvt_pk_bf16_f32 v164, v164, v165
	v_cvt_pk_bf16_f32 v165, v166, v167
	v_cvt_pk_bf16_f32 v166, v56, v57
	v_cvt_pk_bf16_f32 v167, v58, v59
	v_cvt_pk_bf16_f32 v198, v60, v61
	v_cvt_pk_bf16_f32 v199, v62, v63
	v_cvt_pk_bf16_f32 v200, v64, v65
	v_cvt_pk_bf16_f32 v201, v66, v67
	s_waitcnt lgkmcnt(14)
	v_mfma_f32_32x32x16_bf16 v[68:83], v[112:115], v[52:55], v[20:35]
	s_waitcnt lgkmcnt(6)
	v_mfma_f32_32x32x16_bf16 v[52:67], v[112:115], v[96:99], v[36:51]
	v_mfma_f32_32x32x16_bf16 v[68:83], v[160:163], v[84:87], v[68:83]
	s_waitcnt lgkmcnt(4)
	v_mfma_f32_32x32x16_bf16 v[52:67], v[160:163], v[100:103], v[52:67]
	v_mfma_f32_32x32x16_bf16 v[68:83], v[164:167], v[88:91], v[68:83]
	s_waitcnt lgkmcnt(2)
	v_mfma_f32_32x32x16_bf16 v[52:67], v[164:167], v[104:107], v[52:67]
	v_mfma_f32_32x32x16_bf16 v[68:83], v[198:201], v[92:95], v[68:83]
	ds_read_b128 v[84:87], v196
	ds_read_b128 v[88:91], v196 offset:32
	ds_read_b128 v[92:95], v196 offset:64
	ds_read_b128 v[96:99], v196 offset:96
	s_waitcnt lgkmcnt(4)
	v_mfma_f32_32x32x16_bf16 v[52:67], v[198:201], v[108:111], v[52:67]
	ds_read_b128 v[100:103], v196 offset:128
	ds_read_b128 v[104:107], v196 offset:160
	ds_read_b128 v[108:111], v196 offset:192
	ds_read_b128 v[112:115], v196 offset:224
	ds_read_b128 v[160:163], v195
	ds_read_b128 v[164:167], v195 offset:512
	s_waitcnt lgkmcnt(6)
; #define LAS __attribute__((address_space(3)))
; __device__ __forceinline__ int crow(int r, int hi) { return (r & 3) + 8 * (r >> 2) + 4 * hi; }
; __device__ __forceinline__ float swap_max(float m) { auto rr = __builtin_amdgcn_permlane32_swap(__float_as_uint(m), __float_as_uint(m), false, false); return fmaxf(__uint_as_float(rr[0]), __uint_as_float(rr[1])); }
; __device__ __forceinline__ float max3f(float a, float b, float c) { return __builtin_fmaxf(__builtin_fmaxf(a, b), c); }
; #define ATT_LDS_WAIT() asm volatile("s_waitcnt lgkmcnt(0)" ::: "memory")
;     ...
;     for (int d0 = 0; d0 < 4; ++d0) {
;         p0 = __builtin_amdgcn_mfma_f32_32x32x16_bf16(kf[2 * d0], qr[d0], p0, 0, 0, 0);
;         p1 = __builtin_amdgcn_mfma_f32_32x32x16_bf16(kf[2 * d0 + 1], qr[d0], p1, 0, 0, 0);
;     }
;     __builtin_amdgcn_sched_barrier(0);
;     if (LEVEL == 2) { asm volatile("" :: "v"(p0), "v"(p1)); return; }
;     if (masked) {
;         asm volatile("; masked tile" ::: "memory");
; #pragma unroll
;         for (int r = 0; r < 16; ++r) { const int kv = crow(r, hi); if (kv >= qlim) p0[r] = NEG; if (kv + 32 >= qlim) p1[r] = NEG; }
;     }
;     float rm = max3f(p0[0], p1[0], p0[1]), rm2 = max3f(p1[1], p0[2], p1[2]);
; #pragma unroll
;     for (int r = 3; r < 15; r += 2) { rm = max3f(rm, p0[r], p1[r]); rm2 = max3f(rm2, p0[r + 1], p1[r + 1]); }
;     rm = max3f(rm, p0[15], p1[15]); rm = swap_max(max3f(rm, rm2, rm2));
;     if (first || __any(rm > FOX_THR)) {
;         const float dl = first ? rm : fmaxf(rm, 0.f);
;         st.m += dl; st.mq = make_mq(st.m, hi);
; #pragma unroll
;         for (int r = 0; r < 16; ++r) { p0[r] -= dl; p1[r] -= dl; }
;         if (!first) {
;             const float f = __builtin_amdgcn_exp2f(-dl);
;             st.l *= f;
;             if (hi == 0) wsf[r32] = f;
;             ATT_LDS_WAIT();
; #pragma unroll
;             for (int g = 0; g < 4; ++g) { const f32x4 fv = *(const LAS f32x4*)(wsf + 8 * g + 4 * hi);
; #pragma unroll
;                 for (int i = 0; i < 4; ++i) { st.o[0][4 * g + i] *= fv[i]; st.o[1][4 * g + i] *= fv[i]; } }
;         }
	v_mfma_f32_32x32x16_bf16 v[84:99], v[120:123], v[2:5], v[84:99]
	s_waitcnt lgkmcnt(2)
	v_mfma_f32_32x32x16_bf16 v[100:115], v[120:123], v[2:5], v[100:115]
	s_waitcnt lgkmcnt(1)
	v_mfma_f32_32x32x16_bf16 v[84:99], v[160:163], v[6:9], v[84:99]
	s_waitcnt lgkmcnt(0)
	v_mfma_f32_32x32x16_bf16 v[100:115], v[164:167], v[6:9], v[100:115]
	ds_read_b128 v[160:163], v195 offset:2048
	ds_read_b128 v[164:167], v195 offset:2560
	s_waitcnt lgkmcnt(1)
	v_mfma_f32_32x32x16_bf16 v[84:99], v[160:163], v[10:13], v[84:99]
	s_waitcnt lgkmcnt(0)
	v_mfma_f32_32x32x16_bf16 v[100:115], v[164:167], v[10:13], v[100:115]
	ds_read_b128 v[160:163], v195 offset:4096
	ds_read_b128 v[164:167], v195 offset:4608
	s_waitcnt lgkmcnt(1)
	v_mfma_f32_32x32x16_bf16 v[84:99], v[160:163], v[14:17], v[84:99]
	s_waitcnt lgkmcnt(0)
	v_mfma_f32_32x32x16_bf16 v[100:115], v[164:167], v[14:17], v[100:115]
	ds_read_b128 v[160:163], v195 offset:6144
	ds_read_b128 v[164:167], v195 offset:6656
	s_waitcnt lgkmcnt(1)
	v_mfma_f32_32x32x16_bf16 v[84:99], v[160:163], v[116:119], v[84:99]
	s_waitcnt lgkmcnt(0)
	v_mfma_f32_32x32x16_bf16 v[100:115], v[164:167], v[116:119], v[100:115]
	s_nop 11
	v_max_f32_e32 v160, v100, v100
	v_max_f32_e32 v161, v84, v84
	v_max_f32_e32 v160, v161, v160
	v_max3_f32 v161, v101, v86, v102
	v_max3_f32 v160, v160, v85, v87
	v_max3_f32 v161, v161, v88, v104
	v_max3_f32 v160, v160, v103, v89
	v_max3_f32 v161, v161, v90, v106
	v_max3_f32 v160, v160, v105, v91
	v_max3_f32 v161, v161, v92, v108
	v_max3_f32 v160, v160, v107, v93
	v_max3_f32 v161, v161, v94, v110
	v_max3_f32 v160, v160, v109, v95
	v_max3_f32 v161, v161, v96, v112
	v_max3_f32 v160, v160, v111, v97
	v_max3_f32 v161, v161, v98, v114
	v_max3_f32 v160, v160, v113, v99
	v_max3_f32 v160, v160, v115, v161
	v_mov_b32_e32 v161, v160
	s_nop 1
	v_permlane32_swap_b32_e32 v160, v161
	v_max_f32_e32 v161, v161, v161
	v_max_f32_e32 v160, v160, v160
	v_max_f32_e32 v160, v160, v161
	s_mov_b32 s2, 0x41000000
	v_cmp_lt_f32_e32 vcc, s2, v160
	s_cbranch_vccz .LBB0_976
	v_max_f32_e32 v160, 0, v160
	v_exp_f32_e64 v161, -v160
	s_and_saveexec_b64 s[2:3], s[6:7]
	ds_write_b32 v184, v161
	s_or_b64 exec, exec, s[2:3]
	v_add_f32_e32 v191, v191, v160
	v_cvt_pk_bf16_f32 v3, v191, 0
	v_lshlrev_b32_e32 v3, 16, v3
	v_sub_f32_e32 v4, v191, v3
	v_cvt_pk_bf16_f32 v162, v4, 0
	v_lshlrev_b32_e32 v162, 16, v162
	v_sub_f32_e32 v4, v4, v162
	s_waitcnt lgkmcnt(0)
	v_add_u32_e32 v197, s89, v174
	v_cvt_pk_bf16_f32 v4, v162, v4
	v_pk_add_f32 v[84:85], v[84:85], v[160:161] op_sel_hi:[1,0] neg_lo:[0,1] neg_hi:[0,1]
	v_pk_add_f32 v[100:101], v[100:101], v[160:161] op_sel_hi:[1,0] neg_lo:[0,1] neg_hi:[0,1]
	v_pk_add_f32 v[86:87], v[86:87], v[160:161] op_sel_hi:[1,0] neg_lo:[0,1] neg_hi:[0,1]
	v_pk_add_f32 v[102:103], v[102:103], v[160:161] op_sel_hi:[1,0] neg_lo:[0,1] neg_hi:[0,1]
	v_pk_add_f32 v[88:89], v[88:89], v[160:161] op_sel_hi:[1,0] neg_lo:[0,1] neg_hi:[0,1]
	v_pk_add_f32 v[104:105], v[104:105], v[160:161] op_sel_hi:[1,0] neg_lo:[0,1] neg_hi:[0,1]
	v_pk_add_f32 v[90:91], v[90:91], v[160:161] op_sel_hi:[1,0] neg_lo:[0,1] neg_hi:[0,1]
	v_pk_add_f32 v[106:107], v[106:107], v[160:161] op_sel_hi:[1,0] neg_lo:[0,1] neg_hi:[0,1]
	v_pk_add_f32 v[92:93], v[92:93], v[160:161] op_sel_hi:[1,0] neg_lo:[0,1] neg_hi:[0,1]
	v_pk_add_f32 v[108:109], v[108:109], v[160:161] op_sel_hi:[1,0] neg_lo:[0,1] neg_hi:[0,1]
	v_pk_add_f32 v[94:95], v[94:95], v[160:161] op_sel_hi:[1,0] neg_lo:[0,1] neg_hi:[0,1]
	v_pk_add_f32 v[110:111], v[110:111], v[160:161] op_sel_hi:[1,0] neg_lo:[0,1] neg_hi:[0,1]
	v_pk_add_f32 v[96:97], v[96:97], v[160:161] op_sel_hi:[1,0] neg_lo:[0,1] neg_hi:[0,1]
	v_pk_add_f32 v[112:113], v[112:113], v[160:161] op_sel_hi:[1,0] neg_lo:[0,1] neg_hi:[0,1]
	v_pk_add_f32 v[98:99], v[98:99], v[160:161] op_sel_hi:[1,0] neg_lo:[0,1] neg_hi:[0,1]
	v_pk_add_f32 v[114:115], v[114:115], v[160:161] op_sel_hi:[1,0] neg_lo:[0,1] neg_hi:[0,1]
	v_mul_f32_e32 v194, v194, v161
	ds_read_b128 v[160:163], v197
	ds_read_b128 v[164:167], v197 offset:32
	ds_read_b128 v[198:201], v197 offset:64
	ds_read_b128 v[202:205], v197 offset:96
	v_cvt_pk_bf16_f32 v3, 1.0, v3
	v_cndmask_b32_e64 v4, 0, v4, s[6:7]
	v_cndmask_b32_e64 v3, 0, v3, s[6:7]
	s_waitcnt lgkmcnt(1)
	v_pk_mul_f32 v[76:77], v[76:77], v[198:199]
	s_waitcnt lgkmcnt(0)
	v_pk_mul_f32 v[80:81], v[80:81], v[202:203]
	v_pk_mul_f32 v[72:73], v[72:73], v[164:165]
	v_pk_mul_f32 v[82:83], v[82:83], v[204:205]
	v_pk_mul_f32 v[78:79], v[78:79], v[200:201]
	v_pk_mul_f32 v[74:75], v[74:75], v[166:167]
	v_pk_mul_f32 v[70:71], v[70:71], v[162:163]
	v_pk_mul_f32 v[68:69], v[68:69], v[160:161]
	v_pk_mul_f32 v[64:65], v[64:65], v[202:203]
	v_pk_mul_f32 v[60:61], v[60:61], v[198:199]
	v_pk_mul_f32 v[56:57], v[56:57], v[164:165]
	v_pk_mul_f32 v[66:67], v[66:67], v[204:205]
	v_pk_mul_f32 v[62:63], v[62:63], v[200:201]
	v_pk_mul_f32 v[58:59], v[58:59], v[166:167]
	v_pk_mul_f32 v[54:55], v[54:55], v[162:163]
	v_pk_mul_f32 v[52:53], v[52:53], v[160:161]

; #define LAS __attribute__((address_space(3)))
; #define ATT_WAIT_BAR() asm volatile("s_waitcnt vmcnt(0) lgkmcnt(0)\n\ts_barrier" ::: "memory")
; __device__ __forceinline__ void prompt_unit_fox(const Args& a, int l, int b, int h, int qb, LAS unsigned char* lds) {
;     ...
;         ATT_WAIT_BAR();
;         if (jp >= 1) ATT_DMA2(jp - 1, slot == 2 ? 0 : slot + 1);
;         const lds_cptr kslot = (lds_cptr)lds + F_K + slot * 16384; const lds_cptr vp = vp0 + slot * 16384;
;         const LAS float* ck0 = (const LAS float*)(lds + F_CK) + (2 * jp) * 64 + 4 * hi;
;         if (pending) { fox_pair_pv(st, pp, vp0 + pslot * 16384); pending = false; }
;         if (jp < jpd) {
;             bool careful = false;
; #pragma unroll 1
;             for (int pass = 0; pass < 2; ++pass) { if (fox_pair_qs(st, pp, kslot, qr, (const LAS u32x2*)(lds + F_AUG) + (2 * jp) * 64 + r32, careful, r32, hi, wsf)) break; careful = true; }
;             if (lateB) { pending = true; pslot = slot; } else fox_pair_pv(st, pp, vp);
;         } else if (jp == jpd) {
;             if (jd & 1) { fox_tile(st, kslot + 8192, vp + 8192, qr, ck0 + 64, true, true, qlim, r32, hi, wsf); fox_tile(st, kslot, vp, qr, ck0, false, false, qlim, r32, hi, wsf); }
;             else fox_tile(st, kslot, vp, qr, ck0, true, true, qlim, r32, hi, wsf);
;         }
;         slot = (slot == 2) ? 0 : slot + 1;
;     }
.LBB0_997:
.LBB0_998:
	s_add_i32 s33, s93, 1
	s_cmp_lg_u32 s93, 2
	s_cselect_b32 s93, s33, 0
	s_add_i32 s33, s78, -1
	s_cmp_lt_i32 s78, 1
	s_cbranch_scc1 .LBB0_1010
	v_mov_b64_e32 v[156:157], v[160:161]
	s_mov_b32 s78, s33
	v_mov_b64_e32 v[158:159], v[162:163]
	v_mov_b32_e32 v192, v194
	v_mov_b32_e32 v193, v191
	s_branch .LBB0_964

; __device__ __forceinline__ void fox_pair_pv(FoxState& st, const PairP& pp, lds_cptr vpB) {
;     { VFrags vf; vfrags(vf, vpB + 8192); pv(st.o, vf, pp.w[0], pp.w[1], pp.w[2], pp.w[3]); }
;     { VFrags vf; vfrags(vf, vpB); pv(st.o, vf, pp.w[4], pp.w[5], pp.w[6], pp.w[7]); }
; }
; __device__ __forceinline__ void prompt_unit_fox(const Args& a, int l, int b, int h, int qb, LAS unsigned char* lds) {
;     ...
;         slot = (slot == 2) ? 0 : slot + 1;
;     }
;     ...
;     if (pending) fox_pair_pv(st, pp, vp0 + pslot * 16384);
.LBB0_1010:
	s_nop 11
	v_mov_b64_e32 v[68:69], v[20:21]
	v_mov_b64_e32 v[70:71], v[22:23]
	v_mov_b64_e32 v[72:73], v[24:25]
	v_mov_b64_e32 v[74:75], v[26:27]
	v_mov_b64_e32 v[76:77], v[28:29]
	v_mov_b64_e32 v[78:79], v[30:31]
	v_mov_b64_e32 v[80:81], v[32:33]
	v_mov_b64_e32 v[82:83], v[34:35]
	v_mov_b64_e32 v[52:53], v[36:37]
	v_mov_b64_e32 v[54:55], v[38:39]
	v_mov_b64_e32 v[56:57], v[40:41]
	v_mov_b64_e32 v[58:59], v[42:43]
	v_mov_b64_e32 v[60:61], v[44:45]
	v_mov_b64_e32 v[62:63], v[46:47]
	v_mov_b64_e32 v[64:65], v[48:49]
	v_mov_b64_e32 v[66:67], v[50:51]
	s_and_b64 vcc, exec, s[2:3]
	s_cbranch_vccz .LBB0_1012
	v_lshl_add_u32 v2, s75, 14, v175
	ds_read_b64_tr_b16 v[6:7], v2 offset:57344
	ds_read_b64_tr_b16 v[8:9], v2 offset:57856
	ds_read_b64_tr_b16 v[10:11], v2 offset:58368
	ds_read_b64_tr_b16 v[12:13], v2 offset:58880
	s_waitcnt lgkmcnt(2)
	v_mfma_f32_32x32x16_bf16 v[68:83], v[152:155], v[6:9], v[68:83]
	ds_read_b64_tr_b16 v[6:7], v2 offset:61440
	ds_read_b64_tr_b16 v[8:9], v2 offset:61952
	ds_read_b64_tr_b16 v[14:15], v2 offset:62464
	ds_read_b64_tr_b16 v[16:17], v2 offset:62976
	s_waitcnt lgkmcnt(2)
	v_mfma_f32_32x32x16_bf16 v[52:67], v[152:155], v[6:9], v[52:67]
	v_mfma_f32_32x32x16_bf16 v[68:83], v[148:151], v[10:13], v[68:83]
	ds_read_b64_tr_b16 v[6:7], v2 offset:59392
	ds_read_b64_tr_b16 v[8:9], v2 offset:59904
	ds_read_b64_tr_b16 v[10:11], v2 offset:60416
	ds_read_b64_tr_b16 v[12:13], v2 offset:60928
	s_waitcnt lgkmcnt(4)
	v_mfma_f32_32x32x16_bf16 v[52:67], v[148:151], v[14:17], v[52:67]
	s_waitcnt lgkmcnt(2)
	v_mfma_f32_32x32x16_bf16 v[68:83], v[144:147], v[6:9], v[68:83]
	ds_read_b64_tr_b16 v[6:7], v2 offset:63488
	ds_read_b64_tr_b16 v[8:9], v2 offset:64000
	ds_read_b64_tr_b16 v[14:15], v2 offset:64512
	ds_read_b64_tr_b16 v[16:17], v2 offset:65024
	s_waitcnt lgkmcnt(2)
	v_mfma_f32_32x32x16_bf16 v[52:67], v[144:147], v[6:9], v[52:67]
	v_mfma_f32_32x32x16_bf16 v[68:83], v[140:143], v[10:13], v[68:83]
	ds_read_b64_tr_b16 v[6:7], v2 offset:49152
	ds_read_b64_tr_b16 v[8:9], v2 offset:49664
	ds_read_b64_tr_b16 v[10:11], v2 offset:50176
	ds_read_b64_tr_b16 v[12:13], v2 offset:50688
	s_waitcnt lgkmcnt(4)
	v_mfma_f32_32x32x16_bf16 v[52:67], v[140:143], v[14:17], v[52:67]
	s_waitcnt lgkmcnt(2)
	v_mfma_f32_32x32x16_bf16 v[68:83], v[136:139], v[6:9], v[68:83]
	ds_read_b64_tr_b16 v[6:7], v2 offset:53248
	ds_read_b64_tr_b16 v[8:9], v2 offset:53760
	ds_read_b64_tr_b16 v[14:15], v2 offset:54272
	ds_read_b64_tr_b16 v[16:17], v2 offset:54784
	s_waitcnt lgkmcnt(2)
	v_mfma_f32_32x32x16_bf16 v[52:67], v[136:139], v[6:9], v[52:67]
	v_mfma_f32_32x32x16_bf16 v[68:83], v[132:135], v[10:13], v[68:83]
	ds_read_b64_tr_b16 v[6:7], v2 offset:51200
	ds_read_b64_tr_b16 v[8:9], v2 offset:51712
	ds_read_b64_tr_b16 v[10:11], v2 offset:52224
	ds_read_b64_tr_b16 v[12:13], v2 offset:52736
	s_waitcnt lgkmcnt(4)
	v_mfma_f32_32x32x16_bf16 v[52:67], v[132:135], v[14:17], v[52:67]
	s_waitcnt lgkmcnt(2)
	v_mfma_f32_32x32x16_bf16 v[68:83], v[128:131], v[6:9], v[68:83]
	ds_read_b64_tr_b16 v[6:7], v2 offset:55296
	ds_read_b64_tr_b16 v[8:9], v2 offset:55808
	ds_read_b64_tr_b16 v[14:15], v2 offset:56320
	ds_read_b64_tr_b16 v[16:17], v2 offset:56832
	s_waitcnt lgkmcnt(2)
	v_mfma_f32_32x32x16_bf16 v[52:67], v[128:131], v[6:9], v[52:67]
	v_mfma_f32_32x32x16_bf16 v[68:83], v[124:127], v[10:13], v[68:83]
	s_waitcnt lgkmcnt(0)
	v_mfma_f32_32x32x16_bf16 v[52:67], v[124:127], v[14:17], v[52:67]
